# prompt-group attention item: V-tile loads issued right after the K-tile loads into registers proven dead across the whole queue region (linear read-before-write scan of every item kind)
# speedup vs baseline: 1.0010x; 1.0010x over previous
.LBB0_1210:
	v_mov_b32_e32 v164, v0
	s_sub_i32 s0, s14, s13
	v_ashrrev_i32_e32 v66, 5, v164
	v_lshlrev_b32_e32 v2, 2, v164
	v_ashrrev_i32_e32 v67, 31, v66
	v_and_b32_e32 v98, 0x7c, v2
	v_lshlrev_b64 v[2:3], 11, v[66:67]
	v_add_u32_e32 v67, 0x200, v164
	v_ashrrev_i32_e32 v68, 5, v67
	v_ashrrev_i32_e32 v69, 31, v68
	v_lshlrev_b64 v[4:5], 11, v[68:69]
	v_add_u32_e32 v69, 0x400, v164
	v_ashrrev_i32_e32 v70, 5, v69
	s_addk_i32 s0, 0xff60
	v_ashrrev_i32_e32 v71, 31, v70
	s_ashr_i32 s4, s0, 5
	v_lshlrev_b64 v[10:11], 11, v[70:71]
	v_add_u32_e32 v71, 0x600, v164
	s_ashr_i32 s5, s4, 31
	s_lshl_b32 s6, s14, 8
	v_ashrrev_i32_e32 v72, 5, v71
	s_lshl_b64 s[0:1], s[4:5], 11
	s_and_b32 s6, s6, 0x700
	v_ashrrev_i32_e32 v73, 31, v72
	s_or_b32 s0, s0, s6
	s_lshl_b32 s6, s14, 4
	v_lshlrev_b64 v[12:13], 11, v[72:73]
	v_add_u32_e32 v73, 0x800, v164
	s_and_b32 s7, s6, 0x180
	s_lshl_b64 s[4:5], s[4:5], 19
	v_ashrrev_i32_e32 v74, 5, v73
	s_add_u32 s6, s52, s4
	v_ashrrev_i32_e32 v75, 31, v74
	s_addc_u32 s15, s53, s5
	s_lshl_b32 s16, s7, 2
	v_lshlrev_b64 v[18:19], 11, v[74:75]
	v_add_u32_e32 v75, 0xa00, v164
	s_add_u32 s14, s6, s16
	v_ashrrev_i32_e32 v76, 5, v75
	s_addc_u32 s15, s15, 0
	v_lshlrev_b32_e32 v162, 2, v98
	v_ashrrev_i32_e32 v77, 31, v76
	v_lshl_add_u64 v[62:63], s[14:15], 0, v[162:163]
	v_lshlrev_b64 v[20:21], 11, v[76:77]
	v_add_u32_e32 v77, 0xc00, v164
	v_lshl_add_u64 v[2:3], v[62:63], 0, v[2:3]
	v_lshl_add_u64 v[6:7], v[62:63], 0, v[4:5]
	v_ashrrev_i32_e32 v78, 5, v77
	s_lshl_b64 s[14:15], s[0:1], 10
	s_add_u32 s14, s41, s14
	s_addc_u32 s15, s42, s15
	s_add_u32 s14, s14, s7
	s_addc_u32 s15, s15, 0
	s_add_u32 s14, s14, s7
	s_addc_u32 s15, s15, 0
	v_lshrrev_b32_e32 v104, 6, v164
	v_and_b32_e32 v105, 31, v164
	v_lshl_or_b32 v104, v104, 5, v105
	v_bfe_u32 v105, v164, 5, 1
	v_lshlrev_b32_e32 v104, 10, v104
	v_lshl_add_u32 v104, v105, 4, v104
	global_load_dwordx4 v[100:103], v104, s[14:15]
	global_load_dwordx4 v[154:157], v104, s[14:15] offset:32
	global_load_dwordx4 v[150:153], v104, s[14:15] offset:64
	global_load_dwordx4 v[146:149], v104, s[14:15] offset:96
	global_load_dwordx4 v[142:145], v104, s[14:15] offset:128
	global_load_dwordx4 v[138:141], v104, s[14:15] offset:160
	global_load_dwordx4 v[134:137], v104, s[14:15] offset:192
	global_load_dwordx4 v[130:133], v104, s[14:15] offset:224
	s_barrier
	global_load_dwordx4 v[2:5], v[2:3], off
	s_nop 0
	global_load_dwordx4 v[6:9], v[6:7], off
	v_ashrrev_i32_e32 v79, 31, v78
	v_lshl_add_u64 v[10:11], v[62:63], 0, v[10:11]
	v_lshl_add_u64 v[14:15], v[62:63], 0, v[12:13]
	v_lshlrev_b64 v[26:27], 11, v[78:79]
	v_add_u32_e32 v79, 0xe00, v164
	global_load_dwordx4 v[10:13], v[10:11], off
	s_nop 0
	global_load_dwordx4 v[14:17], v[14:15], off
	v_ashrrev_i32_e32 v80, 5, v79
	v_lshl_add_u64 v[18:19], v[62:63], 0, v[18:19]
	v_lshl_add_u64 v[22:23], v[62:63], 0, v[20:21]
	v_ashrrev_i32_e32 v81, 31, v80
	v_add_u32_e32 v34, 0x1000, v164
	v_add_u32_e32 v36, 0x1200, v164
	global_load_dwordx4 v[18:21], v[18:19], off
	s_nop 0
	global_load_dwordx4 v[22:25], v[22:23], off
	v_lshlrev_b64 v[28:29], 11, v[80:81]
	v_ashrrev_i32_e32 v82, 5, v34
	v_ashrrev_i32_e32 v84, 5, v36
	v_lshl_add_u64 v[26:27], v[62:63], 0, v[26:27]
	s_waitcnt vmcnt(30)
	v_lshl_add_u64 v[30:31], v[62:63], 0, v[28:29]
	v_ashrrev_i32_e32 v83, 31, v82
	v_ashrrev_i32_e32 v85, 31, v84
	s_waitcnt vmcnt(28)
	v_add_u32_e32 v42, 0x1400, v164
	s_waitcnt vmcnt(22)
	v_add_u32_e32 v44, 0x1600, v164
	global_load_dwordx4 v[26:29], v[26:27], off
	s_nop 0
	global_load_dwordx4 v[30:33], v[30:31], off
	v_lshlrev_b64 v[34:35], 11, v[82:83]
	v_lshlrev_b64 v[36:37], 11, v[84:85]
	v_ashrrev_i32_e32 v86, 5, v42
	v_ashrrev_i32_e32 v88, 5, v44
	s_waitcnt vmcnt(22)
	v_add_u32_e32 v50, 0x1800, v164
	v_lshl_add_u64 v[34:35], v[62:63], 0, v[34:35]
	v_lshl_add_u64 v[38:39], v[62:63], 0, v[36:37]
	v_ashrrev_i32_e32 v87, 31, v86
	v_ashrrev_i32_e32 v89, 31, v88
	v_ashrrev_i32_e32 v90, 5, v50
	v_add_u32_e32 v54, 0x1a00, v164
	global_load_dwordx4 v[34:37], v[34:35], off
	s_nop 0
	global_load_dwordx4 v[38:41], v[38:39], off
	v_lshlrev_b64 v[42:43], 11, v[86:87]
	s_waitcnt vmcnt(23)
	v_lshlrev_b64 v[44:45], 11, v[88:89]
	v_ashrrev_i32_e32 v91, 31, v90
	v_ashrrev_i32_e32 v92, 5, v54
	v_add_u32_e32 v58, 0x1c00, v164
	v_lshl_add_u64 v[42:43], v[62:63], 0, v[42:43]
	s_waitcnt vmcnt(20)
	v_lshl_add_u64 v[46:47], v[62:63], 0, v[44:45]
	v_lshlrev_b64 v[50:51], 11, v[90:91]
	v_ashrrev_i32_e32 v93, 31, v92
	v_ashrrev_i32_e32 v94, 5, v58
	v_add_u32_e32 v64, 0x1e00, v164
	global_load_dwordx4 v[42:45], v[42:43], off
	s_nop 0
	global_load_dwordx4 v[46:49], v[46:47], off
	v_lshl_add_u64 v[50:51], v[62:63], 0, v[50:51]
	v_lshlrev_b64 v[54:55], 11, v[92:93]
	v_ashrrev_i32_e32 v95, 31, v94
	v_ashrrev_i32_e32 v96, 5, v64
	global_load_dwordx4 v[50:53], v[50:51], off
	v_lshl_add_u64 v[54:55], v[62:63], 0, v[54:55]
	v_lshlrev_b64 v[58:59], 11, v[94:95]
	v_ashrrev_i32_e32 v97, 31, v96
	global_load_dwordx4 v[54:57], v[54:55], off
	v_lshl_add_u64 v[58:59], v[62:63], 0, v[58:59]
	v_lshlrev_b64 v[64:65], 11, v[96:97]
	global_load_dwordx4 v[58:61], v[58:59], off
	v_lshl_add_u64 v[62:63], v[62:63], 0, v[64:65]
	global_load_dwordx4 v[62:65], v[62:63], off
	s_add_u32 s4, s72, s4
	s_addc_u32 s5, s73, s5
	v_lshl_add_u32 v98, v98, 1, 0
	s_add_u32 s4, s4, s16
	s_addc_u32 s5, s5, 0
	v_ashrrev_i32_e32 v67, 4, v67
	v_and_b32_e32 v160, 31, v164
	v_readfirstlane_b32 s15, v0
	s_lshr_b32 s14, s15, 6
	s_lshl_b32 s6, s14, 5
	v_bfe_u32 v161, v164, 5, 1
	s_cmpk_lt_u32 s15, 0x200
	v_lshlrev_b32_e32 v158, 4, v161
	v_ashrrev_i32_e32 v106, 4, v164
	v_and_b32_e32 v180, -2, v106
	v_or_b32_e32 v182, 1, v106
	v_ashrrev_i32_e32 v181, 31, v180
	v_ashrrev_i32_e32 v183, 31, v182
	v_lshl_add_u64 v[236:237], s[4:5], 0, v[162:163]
	v_lshlrev_b64 v[180:181], 11, v[180:181]
	v_lshlrev_b64 v[182:183], 11, v[182:183]
	v_lshl_add_u64 v[180:181], v[236:237], 0, v[180:181]
	v_lshl_add_u64 v[184:185], v[236:237], 0, v[182:183]
	global_load_dwordx4 v[180:183], v[180:181], off
	s_nop 0
	global_load_dwordx4 v[184:187], v[184:185], off
	v_and_b32_e32 v188, -2, v67
	v_or_b32_e32 v190, 1, v67
	v_ashrrev_i32_e32 v189, 31, v188
	v_ashrrev_i32_e32 v191, 31, v190
	v_lshlrev_b64 v[188:189], 11, v[188:189]
	v_lshlrev_b64 v[190:191], 11, v[190:191]
	v_lshl_add_u64 v[188:189], v[236:237], 0, v[188:189]
	v_lshl_add_u64 v[192:193], v[236:237], 0, v[190:191]
	global_load_dwordx4 v[188:191], v[188:189], off
	s_nop 0
	global_load_dwordx4 v[192:195], v[192:193], off
	v_ashrrev_i32_e32 v107, 4, v69
	v_and_b32_e32 v196, -2, v107
	v_or_b32_e32 v198, 1, v107
	v_ashrrev_i32_e32 v197, 31, v196
	v_ashrrev_i32_e32 v199, 31, v198
	v_lshlrev_b64 v[196:197], 11, v[196:197]
	v_lshlrev_b64 v[198:199], 11, v[198:199]
	v_lshl_add_u64 v[196:197], v[236:237], 0, v[196:197]
	v_lshl_add_u64 v[200:201], v[236:237], 0, v[198:199]
	global_load_dwordx4 v[196:199], v[196:197], off
	s_nop 0
	global_load_dwordx4 v[200:203], v[200:201], off
	v_ashrrev_i32_e32 v108, 4, v71
	v_and_b32_e32 v204, -2, v108
	v_or_b32_e32 v206, 1, v108
	v_ashrrev_i32_e32 v205, 31, v204
	v_ashrrev_i32_e32 v207, 31, v206
	v_lshlrev_b64 v[204:205], 11, v[204:205]
	v_lshlrev_b64 v[206:207], 11, v[206:207]
	v_lshl_add_u64 v[204:205], v[236:237], 0, v[204:205]
	v_lshl_add_u64 v[208:209], v[236:237], 0, v[206:207]
	global_load_dwordx4 v[204:207], v[204:205], off
	s_nop 0
	global_load_dwordx4 v[208:211], v[208:209], off
	v_ashrrev_i32_e32 v109, 4, v73
	v_and_b32_e32 v212, -2, v109
	v_or_b32_e32 v214, 1, v109
	v_ashrrev_i32_e32 v213, 31, v212
	v_ashrrev_i32_e32 v215, 31, v214
	v_lshlrev_b64 v[212:213], 11, v[212:213]
	v_lshlrev_b64 v[214:215], 11, v[214:215]
	v_lshl_add_u64 v[212:213], v[236:237], 0, v[212:213]
	v_lshl_add_u64 v[216:217], v[236:237], 0, v[214:215]
	global_load_dwordx4 v[212:215], v[212:213], off
	s_nop 0
	global_load_dwordx4 v[216:219], v[216:217], off
	v_ashrrev_i32_e32 v110, 4, v75
	v_and_b32_e32 v220, -2, v110
	v_or_b32_e32 v222, 1, v110
	v_ashrrev_i32_e32 v221, 31, v220
	v_ashrrev_i32_e32 v223, 31, v222
	v_lshlrev_b64 v[220:221], 11, v[220:221]
	v_lshlrev_b64 v[222:223], 11, v[222:223]
	v_lshl_add_u64 v[220:221], v[236:237], 0, v[220:221]
	v_lshl_add_u64 v[224:225], v[236:237], 0, v[222:223]
	global_load_dwordx4 v[220:223], v[220:221], off
	s_nop 0
	global_load_dwordx4 v[224:227], v[224:225], off
	v_ashrrev_i32_e32 v111, 4, v77
	v_and_b32_e32 v228, -2, v111
	v_or_b32_e32 v230, 1, v111
	v_ashrrev_i32_e32 v229, 31, v228
	v_ashrrev_i32_e32 v231, 31, v230
	v_lshlrev_b64 v[228:229], 11, v[228:229]
	v_lshlrev_b64 v[230:231], 11, v[230:231]
	v_lshl_add_u64 v[228:229], v[236:237], 0, v[228:229]
	v_lshl_add_u64 v[232:233], v[236:237], 0, v[230:231]
	global_load_dwordx4 v[228:231], v[228:229], off
	s_nop 0
	global_load_dwordx4 v[232:235], v[232:233], off
	v_ashrrev_i32_e32 v112, 4, v79
	v_and_b32_e32 v238, -2, v112
	v_or_b32_e32 v240, 1, v112
	v_ashrrev_i32_e32 v239, 31, v238
	v_ashrrev_i32_e32 v241, 31, v240
	v_lshlrev_b64 v[238:239], 11, v[238:239]
	v_lshlrev_b64 v[240:241], 11, v[240:241]
	v_lshl_add_u64 v[238:239], v[236:237], 0, v[238:239]
	v_lshl_add_u64 v[240:241], v[236:237], 0, v[240:241]
	global_load_dwordx4 v[236:239], v[238:239], off
	s_nop 0
	global_load_dwordx4 v[240:243], v[240:241], off
	s_waitcnt vmcnt(31)
	v_cvt_pk_bf16_f32 v2, v2, v3
	v_cvt_pk_bf16_f32 v3, v4, v5
	v_mad_u64_u32 v[4:5], s[16:17], v66, s74, v[98:99]
	ds_write_b64 v4, v[2:3]
	s_waitcnt vmcnt(30)
	v_cvt_pk_bf16_f32 v2, v6, v7
	v_cvt_pk_bf16_f32 v3, v8, v9
	v_mad_u64_u32 v[4:5], s[16:17], v68, s74, v[98:99]
	ds_write_b64 v4, v[2:3]
	s_waitcnt vmcnt(29)
	v_cvt_pk_bf16_f32 v2, v10, v11
	v_cvt_pk_bf16_f32 v3, v12, v13
	v_mad_u64_u32 v[4:5], s[16:17], v70, s74, v[98:99]
	ds_write_b64 v4, v[2:3]
	s_waitcnt vmcnt(28)
	v_cvt_pk_bf16_f32 v2, v14, v15
	v_cvt_pk_bf16_f32 v3, v16, v17
	v_mad_u64_u32 v[4:5], s[16:17], v72, s74, v[98:99]
	ds_write_b64 v4, v[2:3]
	s_waitcnt vmcnt(27)
	v_cvt_pk_bf16_f32 v2, v18, v19
	v_cvt_pk_bf16_f32 v3, v20, v21
	v_mad_u64_u32 v[4:5], s[16:17], v74, s74, v[98:99]
	ds_write_b64 v4, v[2:3]
	s_waitcnt vmcnt(26)
	v_cvt_pk_bf16_f32 v2, v22, v23
	v_cvt_pk_bf16_f32 v3, v24, v25
	v_mad_u64_u32 v[4:5], s[16:17], v76, s74, v[98:99]
	ds_write_b64 v4, v[2:3]
	s_waitcnt vmcnt(25)
	v_cvt_pk_bf16_f32 v2, v26, v27
	v_cvt_pk_bf16_f32 v3, v28, v29
	v_mad_u64_u32 v[4:5], s[16:17], v78, s74, v[98:99]
	ds_write_b64 v4, v[2:3]
	s_waitcnt vmcnt(24)
	v_cvt_pk_bf16_f32 v2, v30, v31
	v_cvt_pk_bf16_f32 v3, v32, v33
	v_mad_u64_u32 v[4:5], s[16:17], v80, s74, v[98:99]
	ds_write_b64 v4, v[2:3]
	s_waitcnt vmcnt(23)
	v_cvt_pk_bf16_f32 v2, v34, v35
	v_cvt_pk_bf16_f32 v3, v36, v37
	v_mad_u64_u32 v[4:5], s[16:17], v82, s74, v[98:99]
	ds_write_b64 v4, v[2:3]
	s_waitcnt vmcnt(22)
	v_cvt_pk_bf16_f32 v2, v38, v39
	v_cvt_pk_bf16_f32 v3, v40, v41
	v_mad_u64_u32 v[4:5], s[16:17], v84, s74, v[98:99]
	ds_write_b64 v4, v[2:3]
	s_waitcnt vmcnt(21)
	v_cvt_pk_bf16_f32 v2, v42, v43
	v_cvt_pk_bf16_f32 v3, v44, v45
	v_mad_u64_u32 v[4:5], s[16:17], v86, s74, v[98:99]
	ds_write_b64 v4, v[2:3]
	s_waitcnt vmcnt(20)
	v_cvt_pk_bf16_f32 v2, v46, v47
	v_cvt_pk_bf16_f32 v3, v48, v49
	v_mad_u64_u32 v[4:5], s[16:17], v88, s74, v[98:99]
	ds_write_b64 v4, v[2:3]
	s_waitcnt vmcnt(19)
	v_cvt_pk_bf16_f32 v2, v50, v51
	v_cvt_pk_bf16_f32 v3, v52, v53
	v_mad_u64_u32 v[4:5], s[16:17], v90, s74, v[98:99]
	ds_write_b64 v4, v[2:3]
	s_waitcnt vmcnt(18)
	v_cvt_pk_bf16_f32 v2, v54, v55
	v_cvt_pk_bf16_f32 v3, v56, v57
	v_mad_u64_u32 v[4:5], s[16:17], v92, s74, v[98:99]
	ds_write_b64 v4, v[2:3]
	s_waitcnt vmcnt(17)
	v_cvt_pk_bf16_f32 v2, v58, v59
	v_cvt_pk_bf16_f32 v3, v60, v61
	v_mad_u64_u32 v[4:5], s[16:17], v94, s74, v[98:99]
	ds_write_b64 v4, v[2:3]
	s_waitcnt vmcnt(16)
	v_cvt_pk_bf16_f32 v2, v62, v63
	v_cvt_pk_bf16_f32 v3, v64, v65
	v_mad_u64_u32 v[4:5], s[16:17], v96, s74, v[98:99]
	ds_write_b64 v4, v[2:3]
	v_lshlrev_b32_e32 v75, 1, v106
	v_lshlrev_b32_e32 v74, 3, v160
	v_and_b32_e32 v76, 8, v75
	v_and_b32_e32 v77, 0x7ffffff0, v106
	v_bitop3_b32 v76, v76, v74, v77 bitop3:0x36
	v_lshlrev_b32_e32 v76, 1, v76
	v_and_b32_e32 v75, 4, v75
	v_add3_u32 v75, s37, v76, v75
	v_and_b32_e32 v106, 8, v106
	s_cselect_b64 s[4:5], -1, 0
	s_waitcnt vmcnt(14)
	v_cvt_pk_bf16_f32 v180, v180, v184
	v_mul_u32_u24_e32 v184, 0x840, v160
	v_add3_u32 v106, v75, v106, v184
	v_cvt_pk_bf16_f32 v181, v181, v185
	ds_write2_b32 v106, v180, v181 offset1:132
	v_cvt_pk_bf16_f32 v180, v182, v186
	v_cvt_pk_bf16_f32 v181, v183, v187
	v_add_u32_e32 v182, 0x400, v106
	ds_write2_b32 v182, v180, v181 offset0:8 offset1:140
	v_lshlrev_b32_e32 v180, 1, v67
	v_and_b32_e32 v181, 8, v180
	v_and_b32_e32 v182, 0x7ffffff0, v67
	v_bitop3_b32 v181, v181, v74, v182 bitop3:0x36
	v_lshlrev_b32_e32 v181, 1, v181
	v_and_b32_e32 v180, 4, v180
	v_add3_u32 v180, s37, v181, v180
	v_and_b32_e32 v181, 8, v67
	s_waitcnt vmcnt(12)
	v_cvt_pk_bf16_f32 v182, v188, v192
	v_add3_u32 v180, v180, v181, v184
	v_cvt_pk_bf16_f32 v181, v189, v193
	ds_write2_b32 v180, v182, v181 offset1:132
	v_cvt_pk_bf16_f32 v181, v190, v194
	v_cvt_pk_bf16_f32 v182, v191, v195
	v_add_u32_e32 v180, 0x400, v180
	ds_write2_b32 v180, v181, v182 offset0:8 offset1:140
	v_lshlrev_b32_e32 v180, 1, v107
	v_and_b32_e32 v181, 8, v180
	v_and_b32_e32 v182, 0x7ffffff0, v107
	v_bitop3_b32 v181, v181, v74, v182 bitop3:0x36
	v_lshlrev_b32_e32 v181, 1, v181
	v_and_b32_e32 v180, 4, v180
	v_add3_u32 v180, s37, v181, v180
	v_and_b32_e32 v181, 8, v107
	s_waitcnt vmcnt(10)
	v_cvt_pk_bf16_f32 v182, v196, v200
	v_add3_u32 v180, v180, v181, v184
	v_cvt_pk_bf16_f32 v181, v197, v201
	ds_write2_b32 v180, v182, v181 offset1:132
	v_cvt_pk_bf16_f32 v181, v198, v202
	v_cvt_pk_bf16_f32 v182, v199, v203
	v_add_u32_e32 v180, 0x400, v180
	ds_write2_b32 v180, v181, v182 offset0:8 offset1:140
	v_lshlrev_b32_e32 v180, 1, v108
	v_and_b32_e32 v181, 8, v180
	v_and_b32_e32 v182, 0x7ffffff0, v108
	v_bitop3_b32 v181, v181, v74, v182 bitop3:0x36
	v_lshlrev_b32_e32 v181, 1, v181
	v_and_b32_e32 v180, 4, v180
	v_add3_u32 v180, s37, v181, v180
	v_and_b32_e32 v181, 8, v108
	s_waitcnt vmcnt(8)
	v_cvt_pk_bf16_f32 v182, v204, v208
	v_add3_u32 v180, v180, v181, v184
	v_cvt_pk_bf16_f32 v181, v205, v209
	ds_write2_b32 v180, v182, v181 offset1:132
	v_cvt_pk_bf16_f32 v181, v206, v210
	v_cvt_pk_bf16_f32 v182, v207, v211
	v_add_u32_e32 v180, 0x400, v180
	ds_write2_b32 v180, v181, v182 offset0:8 offset1:140
	v_lshlrev_b32_e32 v180, 1, v109
	v_and_b32_e32 v181, 8, v180
	v_and_b32_e32 v182, 0x7ffffff0, v109
	v_bitop3_b32 v181, v181, v74, v182 bitop3:0x36
	v_lshlrev_b32_e32 v181, 1, v181
	v_and_b32_e32 v180, 4, v180
	v_add3_u32 v180, s37, v181, v180
	v_and_b32_e32 v181, 8, v109
	s_waitcnt vmcnt(6)
	v_cvt_pk_bf16_f32 v182, v212, v216
	v_add3_u32 v180, v180, v181, v184
	v_cvt_pk_bf16_f32 v181, v213, v217
	ds_write2_b32 v180, v182, v181 offset1:132
	v_cvt_pk_bf16_f32 v181, v214, v218
	v_cvt_pk_bf16_f32 v182, v215, v219
	v_add_u32_e32 v180, 0x400, v180
	ds_write2_b32 v180, v181, v182 offset0:8 offset1:140
	v_lshlrev_b32_e32 v180, 1, v110
	v_and_b32_e32 v181, 8, v180
	v_and_b32_e32 v182, 0x7ffffff0, v110
	v_bitop3_b32 v181, v181, v74, v182 bitop3:0x36
	v_lshlrev_b32_e32 v181, 1, v181
	v_and_b32_e32 v180, 4, v180
	v_add3_u32 v180, s37, v181, v180
	v_and_b32_e32 v181, 8, v110
	s_waitcnt vmcnt(4)
	v_cvt_pk_bf16_f32 v182, v220, v224
	v_add3_u32 v180, v180, v181, v184
	v_cvt_pk_bf16_f32 v181, v221, v225
	ds_write2_b32 v180, v182, v181 offset1:132
	v_cvt_pk_bf16_f32 v181, v222, v226
	v_cvt_pk_bf16_f32 v182, v223, v227
	v_add_u32_e32 v180, 0x400, v180
	ds_write2_b32 v180, v181, v182 offset0:8 offset1:140
	v_lshlrev_b32_e32 v180, 1, v111
	v_and_b32_e32 v181, 8, v180
	v_and_b32_e32 v182, 0x7ffffff0, v111
	v_bitop3_b32 v181, v181, v74, v182 bitop3:0x36
	v_lshlrev_b32_e32 v181, 1, v181
	v_and_b32_e32 v180, 4, v180
	v_add3_u32 v180, s37, v181, v180
	v_and_b32_e32 v181, 8, v111
	s_waitcnt vmcnt(2)
	v_cvt_pk_bf16_f32 v182, v228, v232
	v_add3_u32 v180, v180, v181, v184
	v_cvt_pk_bf16_f32 v181, v229, v233
	ds_write2_b32 v180, v182, v181 offset1:132
	v_cvt_pk_bf16_f32 v181, v230, v234
	v_cvt_pk_bf16_f32 v182, v231, v235
	v_add_u32_e32 v180, 0x400, v180
	ds_write2_b32 v180, v181, v182 offset0:8 offset1:140
	v_lshlrev_b32_e32 v180, 1, v112
	v_and_b32_e32 v181, 8, v180
	v_and_b32_e32 v182, 0x7ffffff0, v112
	v_bitop3_b32 v181, v181, v74, v182 bitop3:0x36
	v_lshlrev_b32_e32 v181, 1, v181
	v_and_b32_e32 v180, 4, v180
	v_add3_u32 v180, s37, v181, v180
	v_and_b32_e32 v181, 8, v112
	s_waitcnt vmcnt(0)
	v_cvt_pk_bf16_f32 v182, v236, v240
	v_add3_u32 v180, v180, v181, v184
	v_cvt_pk_bf16_f32 v181, v237, v241
	ds_write2_b32 v180, v182, v181 offset1:132
	v_cvt_pk_bf16_f32 v181, v238, v242
	v_cvt_pk_bf16_f32 v182, v239, v243
	v_add_u32_e32 v180, 0x400, v180
	ds_write2_b32 v180, v181, v182 offset0:8 offset1:140
	v_mov_b32_e32 v180, 0
	s_cmpk_gt_u32 s15, 0x1ff
	s_waitcnt lgkmcnt(0)
	s_barrier
	s_cbranch_scc1 .LBB0_1212
	s_lshl_b64 s[16:17], s[0:1], 10
	s_add_u32 s15, s41, s16
	s_addc_u32 s17, s42, s17
	s_lshl_b32 s16, s7, 1
	s_add_u32 s16, s15, s16
	v_or_b32_e32 v2, s6, v160
	s_addc_u32 s17, s17, 0
	v_lshlrev_b32_e32 v162, 10, v2
	v_lshl_add_u64 v[2:3], s[16:17], 0, v[162:163]
	v_mov_b32_e32 v159, v163
	v_lshl_add_u64 v[2:3], v[2:3], 0, v[158:159]
	v_mov_b32_e32 v50, v100
	v_mov_b32_e32 v51, v101
	v_mov_b32_e32 v52, v102
	v_mov_b32_e32 v53, v103
	s_nop 0
	s_nop 0
	s_nop 0
	s_nop 0
	s_nop 0
	s_nop 0
	s_nop 0
	v_mul_u32_u24_e32 v2, 0x110, v160
	v_add3_u32 v159, 0, v158, v2
	ds_read_b128 v[2:5], v159
	ds_read_b128 v[18:21], v159 offset:32
	s_mov_b32 s15, 0xff61b1e6
	s_waitcnt vmcnt(7) lgkmcnt(1)
	v_mfma_f32_32x32x16_bf16 v[2:17], v[2:5], v[50:53], 0
	s_waitcnt vmcnt(6) lgkmcnt(0)
	v_mfma_f32_32x32x16_bf16 v[2:17], v[18:21], v[154:157], v[2:17]
	ds_read_b128 v[18:21], v159 offset:64
	s_waitcnt vmcnt(5) lgkmcnt(0)
	v_mfma_f32_32x32x16_bf16 v[2:17], v[18:21], v[150:153], v[2:17]
	ds_read_b128 v[18:21], v159 offset:96
	s_waitcnt vmcnt(4) lgkmcnt(0)
	v_mfma_f32_32x32x16_bf16 v[2:17], v[18:21], v[146:149], v[2:17]
	ds_read_b128 v[18:21], v159 offset:128
	s_waitcnt vmcnt(3) lgkmcnt(0)
	v_mfma_f32_32x32x16_bf16 v[2:17], v[18:21], v[142:145], v[2:17]
	ds_read_b128 v[18:21], v159 offset:160
	s_waitcnt vmcnt(2) lgkmcnt(0)
	v_mfma_f32_32x32x16_bf16 v[2:17], v[18:21], v[138:141], v[2:17]
	ds_read_b128 v[18:21], v159 offset:192
	s_waitcnt vmcnt(1) lgkmcnt(0)
	v_mfma_f32_32x32x16_bf16 v[2:17], v[18:21], v[134:137], v[2:17]
	ds_read_b128 v[18:21], v159 offset:224
	s_waitcnt vmcnt(0) lgkmcnt(0)
	v_mfma_f32_32x32x16_bf16 v[2:17], v[18:21], v[130:133], v[2:17]
	ds_read_b128 v[18:21], v159 offset:8704
	ds_read_b128 v[34:37], v159 offset:8736
	s_waitcnt lgkmcnt(1)
	v_mfma_f32_32x32x16_bf16 v[18:33], v[18:21], v[50:53], 0
	s_waitcnt lgkmcnt(0)
	v_mfma_f32_32x32x16_bf16 v[18:33], v[34:37], v[154:157], v[18:33]
	ds_read_b128 v[34:37], v159 offset:8768
	s_waitcnt lgkmcnt(0)
	v_mfma_f32_32x32x16_bf16 v[18:33], v[34:37], v[150:153], v[18:33]
	ds_read_b128 v[34:37], v159 offset:8800
	s_waitcnt lgkmcnt(0)
	v_mfma_f32_32x32x16_bf16 v[18:33], v[34:37], v[146:149], v[18:33]
	ds_read_b128 v[34:37], v159 offset:8832
	s_waitcnt lgkmcnt(0)
	v_mfma_f32_32x32x16_bf16 v[18:33], v[34:37], v[142:145], v[18:33]
	ds_read_b128 v[34:37], v159 offset:8864
	s_waitcnt lgkmcnt(0)
	v_mfma_f32_32x32x16_bf16 v[18:33], v[34:37], v[138:141], v[18:33]
	ds_read_b128 v[34:37], v159 offset:8896
	s_waitcnt lgkmcnt(0)
	v_mfma_f32_32x32x16_bf16 v[18:33], v[34:37], v[134:137], v[18:33]
	ds_read_b128 v[34:37], v159 offset:8928
	s_waitcnt lgkmcnt(0)
	v_mfma_f32_32x32x16_bf16 v[18:33], v[34:37], v[130:133], v[18:33]
	ds_read_b128 v[34:37], v159 offset:17408
	ds_read_b128 v[54:57], v159 offset:17440
	s_waitcnt lgkmcnt(1)
	v_mfma_f32_32x32x16_bf16 v[34:49], v[34:37], v[50:53], 0
	s_waitcnt lgkmcnt(0)
	v_mfma_f32_32x32x16_bf16 v[34:49], v[54:57], v[154:157], v[34:49]
	ds_read_b128 v[54:57], v159 offset:17472
	s_waitcnt lgkmcnt(0)
	v_mfma_f32_32x32x16_bf16 v[34:49], v[54:57], v[150:153], v[34:49]
	ds_read_b128 v[54:57], v159 offset:17504
	s_waitcnt lgkmcnt(0)
	v_mfma_f32_32x32x16_bf16 v[34:49], v[54:57], v[146:149], v[34:49]
	ds_read_b128 v[54:57], v159 offset:17536
	s_waitcnt lgkmcnt(0)
	v_mfma_f32_32x32x16_bf16 v[34:49], v[54:57], v[142:145], v[34:49]
	ds_read_b128 v[54:57], v159 offset:17568
	s_waitcnt lgkmcnt(0)
	v_mfma_f32_32x32x16_bf16 v[34:49], v[54:57], v[138:141], v[34:49]
	ds_read_b128 v[54:57], v159 offset:17600
	s_waitcnt lgkmcnt(0)
	v_mfma_f32_32x32x16_bf16 v[34:49], v[54:57], v[134:137], v[34:49]
	ds_read_b128 v[54:57], v159 offset:17632
	s_waitcnt lgkmcnt(0)
	v_mfma_f32_32x32x16_bf16 v[34:49], v[54:57], v[130:133], v[34:49]
	ds_read_b128 v[54:57], v159 offset:26112
	ds_read_b128 v[58:61], v159 offset:26144
	s_waitcnt lgkmcnt(1)
	v_mfma_f32_32x32x16_bf16 v[114:129], v[54:57], v[50:53], 0
	ds_read_b128 v[54:57], v159 offset:26176
	s_waitcnt lgkmcnt(1)
	v_mfma_f32_32x32x16_bf16 v[114:129], v[58:61], v[154:157], v[114:129]
	s_waitcnt lgkmcnt(0)
	v_mfma_f32_32x32x16_bf16 v[114:129], v[54:57], v[150:153], v[114:129]
	ds_read_b128 v[54:57], v159 offset:26208
	s_waitcnt lgkmcnt(0)
	v_mfma_f32_32x32x16_bf16 v[114:129], v[54:57], v[146:149], v[114:129]
	ds_read_b128 v[54:57], v159 offset:26240
	s_waitcnt lgkmcnt(0)
	v_mfma_f32_32x32x16_bf16 v[114:129], v[54:57], v[142:145], v[114:129]
	ds_read_b128 v[54:57], v159 offset:26272
	s_waitcnt lgkmcnt(0)
	v_mfma_f32_32x32x16_bf16 v[114:129], v[54:57], v[138:141], v[114:129]
	ds_read_b128 v[54:57], v159 offset:26304
	s_waitcnt lgkmcnt(0)
	v_mfma_f32_32x32x16_bf16 v[114:129], v[54:57], v[134:137], v[114:129]
	ds_read_b128 v[54:57], v159 offset:26336
	s_waitcnt lgkmcnt(0)
	v_mfma_f32_32x32x16_bf16 v[114:129], v[54:57], v[130:133], v[114:129]
	ds_read_b128 v[54:57], v159 offset:34816
	ds_read_b128 v[58:61], v159 offset:34848
	s_waitcnt lgkmcnt(1)
	v_mfma_f32_32x32x16_bf16 v[98:113], v[54:57], v[50:53], 0
	ds_read_b128 v[54:57], v159 offset:34880
	s_waitcnt lgkmcnt(1)
	v_mfma_f32_32x32x16_bf16 v[98:113], v[58:61], v[154:157], v[98:113]
	s_waitcnt lgkmcnt(0)
	v_mfma_f32_32x32x16_bf16 v[98:113], v[54:57], v[150:153], v[98:113]
	ds_read_b128 v[54:57], v159 offset:34912
	s_waitcnt lgkmcnt(0)
	v_mfma_f32_32x32x16_bf16 v[98:113], v[54:57], v[146:149], v[98:113]
	ds_read_b128 v[54:57], v159 offset:34944
	s_waitcnt lgkmcnt(0)
	v_mfma_f32_32x32x16_bf16 v[98:113], v[54:57], v[142:145], v[98:113]
	ds_read_b128 v[54:57], v159 offset:34976
	s_waitcnt lgkmcnt(0)
	v_mfma_f32_32x32x16_bf16 v[98:113], v[54:57], v[138:141], v[98:113]
	ds_read_b128 v[54:57], v159 offset:35008
	s_waitcnt lgkmcnt(0)
	v_mfma_f32_32x32x16_bf16 v[98:113], v[54:57], v[134:137], v[98:113]
	ds_read_b128 v[54:57], v159 offset:35040
	s_waitcnt lgkmcnt(0)
	v_mfma_f32_32x32x16_bf16 v[98:113], v[54:57], v[130:133], v[98:113]
	ds_read_b128 v[54:57], v159 offset:43520
	ds_read_b128 v[58:61], v159 offset:43552
	s_waitcnt lgkmcnt(1)
	v_mfma_f32_32x32x16_bf16 v[82:97], v[54:57], v[50:53], 0
	ds_read_b128 v[54:57], v159 offset:43584
	s_waitcnt lgkmcnt(1)
	v_mfma_f32_32x32x16_bf16 v[82:97], v[58:61], v[154:157], v[82:97]
	s_waitcnt lgkmcnt(0)
	v_mfma_f32_32x32x16_bf16 v[82:97], v[54:57], v[150:153], v[82:97]
	ds_read_b128 v[54:57], v159 offset:43616
	s_waitcnt lgkmcnt(0)
	v_mfma_f32_32x32x16_bf16 v[82:97], v[54:57], v[146:149], v[82:97]
	ds_read_b128 v[54:57], v159 offset:43648
	s_waitcnt lgkmcnt(0)
	v_mfma_f32_32x32x16_bf16 v[82:97], v[54:57], v[142:145], v[82:97]
	ds_read_b128 v[54:57], v159 offset:43680
	s_waitcnt lgkmcnt(0)
	v_mfma_f32_32x32x16_bf16 v[82:97], v[54:57], v[138:141], v[82:97]
	ds_read_b128 v[54:57], v159 offset:43712
	s_waitcnt lgkmcnt(0)
	v_mfma_f32_32x32x16_bf16 v[82:97], v[54:57], v[134:137], v[82:97]
	ds_read_b128 v[54:57], v159 offset:43744
	s_waitcnt lgkmcnt(0)
	v_mfma_f32_32x32x16_bf16 v[82:97], v[54:57], v[130:133], v[82:97]
	ds_read_b128 v[54:57], v159 offset:52224
	ds_read_b128 v[58:61], v159 offset:52256
	s_waitcnt lgkmcnt(1)
	v_mfma_f32_32x32x16_bf16 v[66:81], v[54:57], v[50:53], 0
	ds_read_b128 v[54:57], v159 offset:52288
	s_waitcnt lgkmcnt(1)
	v_mfma_f32_32x32x16_bf16 v[66:81], v[58:61], v[154:157], v[66:81]
	s_waitcnt lgkmcnt(0)
	v_mfma_f32_32x32x16_bf16 v[66:81], v[54:57], v[150:153], v[66:81]
	ds_read_b128 v[54:57], v159 offset:52320
	s_waitcnt lgkmcnt(0)
	v_mfma_f32_32x32x16_bf16 v[66:81], v[54:57], v[146:149], v[66:81]
	ds_read_b128 v[54:57], v159 offset:52352
	s_waitcnt lgkmcnt(0)
	v_mfma_f32_32x32x16_bf16 v[66:81], v[54:57], v[142:145], v[66:81]
	ds_read_b128 v[54:57], v159 offset:52384
	s_waitcnt lgkmcnt(0)
	v_mfma_f32_32x32x16_bf16 v[66:81], v[54:57], v[138:141], v[66:81]
	ds_read_b128 v[54:57], v159 offset:52416
	s_waitcnt lgkmcnt(0)
	v_mfma_f32_32x32x16_bf16 v[66:81], v[54:57], v[134:137], v[66:81]
	ds_read_b128 v[54:57], v159 offset:52448
	s_waitcnt lgkmcnt(0)
	v_mfma_f32_32x32x16_bf16 v[66:81], v[54:57], v[130:133], v[66:81]
	ds_read_b128 v[54:57], v159 offset:60928
	ds_read_b128 v[174:177], v159 offset:60960
	s_waitcnt lgkmcnt(1)
	v_mfma_f32_32x32x16_bf16 v[50:65], v[54:57], v[50:53], 0
	s_waitcnt lgkmcnt(0)
	v_mfma_f32_32x32x16_bf16 v[50:65], v[174:177], v[154:157], v[50:65]
	ds_read_b128 v[154:157], v159 offset:60992
	s_waitcnt lgkmcnt(0)
	v_mfma_f32_32x32x16_bf16 v[50:65], v[154:157], v[150:153], v[50:65]
	ds_read_b128 v[150:153], v159 offset:61024
	s_waitcnt lgkmcnt(0)
	v_mfma_f32_32x32x16_bf16 v[50:65], v[150:153], v[146:149], v[50:65]
	ds_read_b128 v[146:149], v159 offset:61056
	s_waitcnt lgkmcnt(0)
	v_mfma_f32_32x32x16_bf16 v[50:65], v[146:149], v[142:145], v[50:65]
	ds_read_b128 v[142:145], v159 offset:61088
	s_waitcnt lgkmcnt(0)
	v_mfma_f32_32x32x16_bf16 v[50:65], v[142:145], v[138:141], v[50:65]
	ds_read_b128 v[138:141], v159 offset:61120
	s_waitcnt lgkmcnt(0)
	v_mfma_f32_32x32x16_bf16 v[50:65], v[138:141], v[134:137], v[50:65]
	ds_read_b128 v[134:137], v159 offset:61152
	s_waitcnt lgkmcnt(0)
	v_mfma_f32_32x32x16_bf16 v[50:65], v[134:137], v[130:133], v[50:65]
	v_max3_f32 v130, v2, s15, v3
	v_max3_f32 v130, v130, v4, v5
	v_max3_f32 v130, v130, v6, v7
	v_max3_f32 v130, v130, v8, v9
	v_max3_f32 v130, v130, v10, v11
	v_max3_f32 v130, v130, v12, v13
	v_max3_f32 v130, v130, v14, v15
	v_max3_f32 v130, v130, v16, v17
	v_max3_f32 v130, v130, v18, v19
	v_max3_f32 v130, v130, v20, v21
	v_max3_f32 v130, v130, v22, v23
	v_max3_f32 v130, v130, v24, v25
	v_max3_f32 v130, v130, v26, v27
	v_max3_f32 v130, v130, v28, v29
	v_max3_f32 v130, v130, v30, v31
	v_max3_f32 v130, v130, v32, v33
	v_max3_f32 v130, v130, v34, v35
	v_max3_f32 v130, v130, v36, v37
	v_max3_f32 v130, v130, v38, v39
	v_max3_f32 v130, v130, v40, v41
	v_max3_f32 v130, v130, v42, v43
	v_max3_f32 v130, v130, v44, v45
	v_max3_f32 v130, v130, v46, v47
	v_max3_f32 v130, v130, v48, v49
	v_max3_f32 v130, v130, v114, v115
	v_max3_f32 v130, v130, v116, v117
	v_max3_f32 v130, v130, v118, v119
	v_max3_f32 v130, v130, v120, v121
	v_max3_f32 v130, v130, v122, v123
	v_max3_f32 v130, v130, v124, v125
	v_max3_f32 v130, v130, v126, v127
	v_max3_f32 v130, v130, v128, v129
	v_max3_f32 v130, v130, v98, v99
	v_max3_f32 v130, v130, v100, v101
	v_max3_f32 v130, v130, v102, v103
	v_max3_f32 v130, v130, v104, v105
	v_max3_f32 v130, v130, v106, v107
	v_max3_f32 v130, v130, v108, v109
	v_max3_f32 v130, v130, v110, v111
	v_max3_f32 v130, v130, v112, v113
	v_max3_f32 v130, v130, v82, v83
	v_max3_f32 v130, v130, v84, v85
	v_max3_f32 v130, v130, v86, v87
	v_max3_f32 v130, v130, v88, v89
	v_max3_f32 v130, v130, v90, v91
	v_max3_f32 v130, v130, v92, v93
	v_max3_f32 v130, v130, v94, v95
	v_max3_f32 v130, v130, v96, v97
	v_max3_f32 v130, v130, v66, v67
	v_max3_f32 v130, v130, v68, v69
	v_max3_f32 v130, v130, v70, v71
	v_max3_f32 v130, v130, v72, v73
	v_max3_f32 v130, v130, v74, v75
	v_max3_f32 v130, v130, v76, v77
	v_max3_f32 v130, v130, v78, v79
	v_max3_f32 v130, v130, v80, v81
	v_max3_f32 v130, v130, v50, v51
	v_max3_f32 v130, v130, v52, v53
	v_max3_f32 v130, v130, v54, v55
	v_max3_f32 v130, v130, v56, v57
	v_and_b32_e32 v132, 64, v1
	v_max3_f32 v130, v130, v58, v59
	v_xor_b32_e32 v131, 32, v1
	v_add_u32_e32 v132, 64, v132
	v_max3_f32 v130, v130, v60, v61
	v_cmp_lt_i32_e32 vcc, v131, v132
	v_max3_f32 v130, v130, v62, v63
	v_max3_f32 v130, v130, v64, v65
	v_cndmask_b32_e32 v131, v1, v131, vcc
	v_lshlrev_b32_e32 v146, 2, v131
	ds_bpermute_b32 v131, v146, v130
	s_waitcnt lgkmcnt(0)
	v_max_f32_e32 v131, v131, v131
	v_max_f32_e32 v147, v130, v131
	v_sub_f32_e32 v2, v2, v147
	v_sub_f32_e32 v3, v3, v147
	v_exp_f32_e32 v2, v2
	v_exp_f32_e32 v3, v3
	v_sub_f32_e32 v4, v4, v147
	v_exp_f32_e32 v4, v4
	v_sub_f32_e32 v5, v5, v147
	v_exp_f32_e32 v5, v5
	v_sub_f32_e32 v6, v6, v147
	v_exp_f32_e32 v6, v6
	v_sub_f32_e32 v7, v7, v147
	v_cvt_pk_bf16_f32 v134, v2, v3
	v_add_f32_e32 v2, 0, v2
	v_exp_f32_e32 v7, v7
	v_sub_f32_e32 v8, v8, v147
	v_add_f32_e32 v2, v3, v2
	v_exp_f32_e32 v8, v8
	v_sub_f32_e32 v9, v9, v147
	v_add_f32_e32 v2, v4, v2
	v_exp_f32_e32 v9, v9
	v_sub_f32_e32 v10, v10, v147
	v_add_f32_e32 v2, v5, v2
	v_exp_f32_e32 v10, v10
	v_sub_f32_e32 v11, v11, v147
	v_add_f32_e32 v2, v6, v2
	v_exp_f32_e32 v11, v11
	v_sub_f32_e32 v12, v12, v147
	v_add_f32_e32 v2, v7, v2
	v_exp_f32_e32 v12, v12
	v_sub_f32_e32 v13, v13, v147
	v_add_f32_e32 v2, v8, v2
	v_exp_f32_e32 v13, v13
	v_sub_f32_e32 v14, v14, v147
	v_add_f32_e32 v2, v9, v2
	v_exp_f32_e32 v14, v14
	v_sub_f32_e32 v15, v15, v147
	v_add_f32_e32 v2, v10, v2
	v_exp_f32_e32 v15, v15
	v_sub_f32_e32 v16, v16, v147
	v_add_f32_e32 v2, v11, v2
	v_exp_f32_e32 v16, v16
	v_sub_f32_e32 v17, v17, v147
	v_add_f32_e32 v2, v12, v2
	v_exp_f32_e32 v17, v17
	v_add_f32_e32 v2, v13, v2
	v_sub_f32_e32 v3, v18, v147
	v_cvt_pk_bf16_f32 v135, v4, v5
	v_add_f32_e32 v2, v14, v2
	v_exp_f32_e32 v3, v3
	v_sub_f32_e32 v4, v19, v147
	v_add_f32_e32 v2, v15, v2
	v_exp_f32_e32 v4, v4
	v_sub_f32_e32 v5, v20, v147
	v_cvt_pk_bf16_f32 v136, v6, v7
	v_add_f32_e32 v2, v16, v2
	v_exp_f32_e32 v5, v5
	v_sub_f32_e32 v6, v21, v147
	v_add_f32_e32 v2, v17, v2
	v_exp_f32_e32 v6, v6
	v_sub_f32_e32 v7, v22, v147
	v_cvt_pk_bf16_f32 v137, v8, v9
	v_exp_f32_e32 v7, v7
	v_sub_f32_e32 v8, v23, v147
	v_add_f32_e32 v2, v3, v2
	v_exp_f32_e32 v8, v8
	v_sub_f32_e32 v9, v24, v147
	v_add_f32_e32 v2, v4, v2
	v_cvt_pk_bf16_f32 v130, v10, v11
	v_exp_f32_e32 v9, v9
	v_sub_f32_e32 v10, v25, v147
	v_add_f32_e32 v2, v5, v2
	v_exp_f32_e32 v10, v10
	v_sub_f32_e32 v11, v26, v147
	v_add_f32_e32 v2, v6, v2
	v_cvt_pk_bf16_f32 v131, v12, v13
	v_exp_f32_e32 v11, v11
	v_sub_f32_e32 v12, v27, v147
	v_add_f32_e32 v2, v7, v2
	v_exp_f32_e32 v12, v12
	v_sub_f32_e32 v13, v28, v147
	v_add_f32_e32 v2, v8, v2
	v_cvt_pk_bf16_f32 v132, v14, v15
	v_exp_f32_e32 v13, v13
	v_sub_f32_e32 v14, v29, v147
	v_add_f32_e32 v2, v9, v2
	v_exp_f32_e32 v14, v14
	v_sub_f32_e32 v15, v30, v147
	v_add_f32_e32 v2, v10, v2
	v_cvt_pk_bf16_f32 v133, v16, v17
	v_exp_f32_e32 v15, v15
	v_sub_f32_e32 v16, v31, v147
	v_add_f32_e32 v2, v11, v2
	v_exp_f32_e32 v16, v16
	v_sub_f32_e32 v17, v32, v147
	v_add_f32_e32 v2, v12, v2
	v_exp_f32_e32 v17, v17
	v_sub_f32_e32 v18, v33, v147
	v_add_f32_e32 v2, v13, v2
	v_exp_f32_e32 v18, v18
	v_cvt_pk_bf16_f32 v142, v3, v4
	v_add_f32_e32 v2, v14, v2
	v_sub_f32_e32 v3, v34, v147
	v_add_f32_e32 v2, v15, v2
	v_exp_f32_e32 v3, v3
	v_sub_f32_e32 v4, v35, v147
	v_cvt_pk_bf16_f32 v143, v5, v6
	v_add_f32_e32 v2, v16, v2
	v_exp_f32_e32 v4, v4
	v_sub_f32_e32 v5, v36, v147
	v_add_f32_e32 v2, v17, v2
	v_exp_f32_e32 v5, v5
	v_sub_f32_e32 v6, v37, v147
	v_cvt_pk_bf16_f32 v144, v7, v8
	v_add_f32_e32 v2, v18, v2
	v_exp_f32_e32 v6, v6
	v_sub_f32_e32 v7, v38, v147
	v_exp_f32_e32 v7, v7
	v_sub_f32_e32 v8, v39, v147
	v_add_f32_e32 v2, v3, v2
	v_cvt_pk_bf16_f32 v145, v9, v10
	v_exp_f32_e32 v8, v8
	v_sub_f32_e32 v9, v40, v147
	v_add_f32_e32 v2, v4, v2
	v_exp_f32_e32 v9, v9
	v_sub_f32_e32 v10, v41, v147
	v_add_f32_e32 v2, v5, v2
	v_cvt_pk_bf16_f32 v138, v11, v12
	v_exp_f32_e32 v10, v10
	v_sub_f32_e32 v11, v42, v147
	v_add_f32_e32 v2, v6, v2
	v_exp_f32_e32 v11, v11
	v_sub_f32_e32 v12, v43, v147
	v_add_f32_e32 v2, v7, v2
	v_cvt_pk_bf16_f32 v139, v13, v14
	v_exp_f32_e32 v12, v12
	v_sub_f32_e32 v13, v44, v147
	v_add_f32_e32 v2, v8, v2
	v_exp_f32_e32 v13, v13
	v_sub_f32_e32 v14, v45, v147
	v_add_f32_e32 v2, v9, v2
	v_cvt_pk_bf16_f32 v140, v15, v16
	v_exp_f32_e32 v14, v14
	v_sub_f32_e32 v15, v46, v147
	v_add_f32_e32 v2, v10, v2
	v_exp_f32_e32 v15, v15
	v_sub_f32_e32 v16, v47, v147
	v_add_f32_e32 v2, v11, v2
	v_cvt_pk_bf16_f32 v141, v17, v18
	v_exp_f32_e32 v16, v16
	v_sub_f32_e32 v17, v48, v147
	v_add_f32_e32 v2, v12, v2
	v_exp_f32_e32 v17, v17
	v_sub_f32_e32 v18, v49, v147
	v_add_f32_e32 v2, v13, v2
	v_exp_f32_e32 v18, v18
	v_cvt_pk_bf16_f32 v38, v3, v4
	v_add_f32_e32 v2, v14, v2
	v_sub_f32_e32 v3, v114, v147
	v_add_f32_e32 v2, v15, v2
	v_exp_f32_e32 v3, v3
	v_sub_f32_e32 v4, v115, v147
	v_cvt_pk_bf16_f32 v39, v5, v6
	v_add_f32_e32 v2, v16, v2
	v_exp_f32_e32 v4, v4
	v_sub_f32_e32 v5, v116, v147
	v_add_f32_e32 v2, v17, v2
	v_exp_f32_e32 v5, v5
	v_sub_f32_e32 v6, v117, v147
	v_cvt_pk_bf16_f32 v40, v7, v8
	v_add_f32_e32 v2, v18, v2
	v_exp_f32_e32 v6, v6
	v_sub_f32_e32 v7, v118, v147
	v_exp_f32_e32 v7, v7
	v_sub_f32_e32 v8, v119, v147
	v_add_f32_e32 v2, v3, v2
	v_cvt_pk_bf16_f32 v41, v9, v10
	v_exp_f32_e32 v8, v8
	v_sub_f32_e32 v9, v120, v147
	v_add_f32_e32 v2, v4, v2
	v_exp_f32_e32 v9, v9
	v_sub_f32_e32 v10, v121, v147
	v_add_f32_e32 v2, v5, v2
	v_cvt_pk_bf16_f32 v34, v11, v12
	v_exp_f32_e32 v10, v10
	v_sub_f32_e32 v11, v122, v147
	v_add_f32_e32 v2, v6, v2
	v_exp_f32_e32 v11, v11
	v_sub_f32_e32 v12, v123, v147
	v_add_f32_e32 v2, v7, v2
	v_cvt_pk_bf16_f32 v35, v13, v14
	v_exp_f32_e32 v12, v12
	v_sub_f32_e32 v13, v124, v147
	v_add_f32_e32 v2, v8, v2
	v_exp_f32_e32 v13, v13
	v_sub_f32_e32 v14, v125, v147
	v_add_f32_e32 v2, v9, v2
	v_cvt_pk_bf16_f32 v36, v15, v16
	v_exp_f32_e32 v14, v14
	v_sub_f32_e32 v15, v126, v147
	v_add_f32_e32 v2, v10, v2
	v_exp_f32_e32 v15, v15
	v_sub_f32_e32 v16, v127, v147
	v_add_f32_e32 v2, v11, v2
	v_cvt_pk_bf16_f32 v37, v17, v18
	v_exp_f32_e32 v16, v16
	v_sub_f32_e32 v17, v128, v147
	v_add_f32_e32 v2, v12, v2
	v_exp_f32_e32 v17, v17
	v_sub_f32_e32 v18, v129, v147
	v_add_f32_e32 v2, v13, v2
	v_exp_f32_e32 v18, v18
	v_cvt_pk_bf16_f32 v46, v3, v4
	v_add_f32_e32 v2, v14, v2
	v_sub_f32_e32 v3, v98, v147
	v_add_f32_e32 v2, v15, v2
	v_exp_f32_e32 v3, v3
	v_sub_f32_e32 v4, v99, v147
	v_cvt_pk_bf16_f32 v47, v5, v6
	v_add_f32_e32 v2, v16, v2
	v_exp_f32_e32 v4, v4
	v_sub_f32_e32 v5, v100, v147
	v_add_f32_e32 v2, v17, v2
	v_exp_f32_e32 v5, v5
	v_sub_f32_e32 v6, v101, v147
	v_cvt_pk_bf16_f32 v48, v7, v8
	v_add_f32_e32 v2, v18, v2
	v_exp_f32_e32 v6, v6
	v_sub_f32_e32 v7, v102, v147
	v_exp_f32_e32 v7, v7
	v_sub_f32_e32 v8, v103, v147
	v_add_f32_e32 v2, v3, v2
	v_cvt_pk_bf16_f32 v49, v9, v10
	v_exp_f32_e32 v8, v8
	v_sub_f32_e32 v9, v104, v147
	v_add_f32_e32 v2, v4, v2
	v_exp_f32_e32 v9, v9
	v_sub_f32_e32 v10, v105, v147
	v_add_f32_e32 v2, v5, v2
	v_cvt_pk_bf16_f32 v42, v11, v12
	v_exp_f32_e32 v10, v10
	v_sub_f32_e32 v11, v106, v147
	v_add_f32_e32 v2, v6, v2
	v_exp_f32_e32 v11, v11
	v_sub_f32_e32 v12, v107, v147
	v_add_f32_e32 v2, v7, v2
	v_cvt_pk_bf16_f32 v43, v13, v14
	v_exp_f32_e32 v12, v12
	v_sub_f32_e32 v13, v108, v147
	v_add_f32_e32 v2, v8, v2
	v_exp_f32_e32 v13, v13
	v_sub_f32_e32 v14, v109, v147
	v_add_f32_e32 v2, v9, v2
	v_cvt_pk_bf16_f32 v44, v15, v16
	v_exp_f32_e32 v14, v14
	v_sub_f32_e32 v15, v110, v147
	v_add_f32_e32 v2, v10, v2
	v_exp_f32_e32 v15, v15
	v_sub_f32_e32 v16, v111, v147
	v_add_f32_e32 v2, v11, v2
	v_cvt_pk_bf16_f32 v45, v17, v18
	v_exp_f32_e32 v16, v16
	v_sub_f32_e32 v17, v112, v147
	v_add_f32_e32 v2, v12, v2
	v_exp_f32_e32 v17, v17
	v_sub_f32_e32 v18, v113, v147
	v_add_f32_e32 v2, v13, v2
	v_exp_f32_e32 v18, v18
	v_cvt_pk_bf16_f32 v102, v3, v4
	v_add_f32_e32 v2, v14, v2
	v_sub_f32_e32 v3, v82, v147
	v_add_f32_e32 v2, v15, v2
	v_exp_f32_e32 v3, v3
	v_sub_f32_e32 v4, v83, v147
	v_cvt_pk_bf16_f32 v103, v5, v6
	v_add_f32_e32 v2, v16, v2
	v_exp_f32_e32 v4, v4
	v_sub_f32_e32 v5, v84, v147
	v_add_f32_e32 v2, v17, v2
	v_exp_f32_e32 v5, v5
	v_sub_f32_e32 v6, v85, v147
	v_cvt_pk_bf16_f32 v104, v7, v8
	v_add_f32_e32 v2, v18, v2
	v_exp_f32_e32 v6, v6
	v_sub_f32_e32 v7, v86, v147
	v_exp_f32_e32 v7, v7
	v_sub_f32_e32 v8, v87, v147
	v_add_f32_e32 v2, v3, v2
	v_cvt_pk_bf16_f32 v105, v9, v10
	v_exp_f32_e32 v8, v8
	v_sub_f32_e32 v9, v88, v147
	v_add_f32_e32 v2, v4, v2
	v_exp_f32_e32 v9, v9
	v_sub_f32_e32 v10, v89, v147
	v_add_f32_e32 v2, v5, v2
	v_cvt_pk_bf16_f32 v98, v11, v12
	v_exp_f32_e32 v10, v10
	v_sub_f32_e32 v11, v90, v147
	v_add_f32_e32 v2, v6, v2
	v_exp_f32_e32 v11, v11
	v_sub_f32_e32 v12, v91, v147
	v_add_f32_e32 v2, v7, v2
	v_cvt_pk_bf16_f32 v99, v13, v14
	v_exp_f32_e32 v12, v12
	v_sub_f32_e32 v13, v92, v147
	v_add_f32_e32 v2, v8, v2
	v_exp_f32_e32 v13, v13
	v_sub_f32_e32 v14, v93, v147
	v_add_f32_e32 v2, v9, v2
	v_cvt_pk_bf16_f32 v100, v15, v16
	v_exp_f32_e32 v14, v14
	v_sub_f32_e32 v15, v94, v147
	v_add_f32_e32 v2, v10, v2
	v_exp_f32_e32 v15, v15
	v_sub_f32_e32 v16, v95, v147
	v_add_f32_e32 v2, v11, v2
	v_cvt_pk_bf16_f32 v101, v17, v18
	v_exp_f32_e32 v16, v16
	v_sub_f32_e32 v17, v96, v147
	v_add_f32_e32 v2, v12, v2
	v_exp_f32_e32 v17, v17
	v_sub_f32_e32 v18, v97, v147
	v_add_f32_e32 v2, v13, v2
	v_exp_f32_e32 v18, v18
	v_cvt_pk_bf16_f32 v86, v3, v4
	v_add_f32_e32 v2, v14, v2
	v_sub_f32_e32 v3, v66, v147
	v_add_f32_e32 v2, v15, v2
	v_exp_f32_e32 v3, v3
	v_sub_f32_e32 v4, v67, v147
	v_cvt_pk_bf16_f32 v87, v5, v6
	v_add_f32_e32 v2, v16, v2
	v_exp_f32_e32 v4, v4
	v_sub_f32_e32 v5, v68, v147
	v_add_f32_e32 v2, v17, v2
	v_exp_f32_e32 v5, v5
	v_sub_f32_e32 v6, v69, v147
	v_cvt_pk_bf16_f32 v88, v7, v8
	v_add_f32_e32 v2, v18, v2
	v_exp_f32_e32 v6, v6
	v_sub_f32_e32 v7, v70, v147
	v_exp_f32_e32 v7, v7
	v_sub_f32_e32 v8, v71, v147
	v_add_f32_e32 v2, v3, v2
	v_cvt_pk_bf16_f32 v89, v9, v10
	v_exp_f32_e32 v8, v8
	v_sub_f32_e32 v9, v72, v147
	v_add_f32_e32 v2, v4, v2
	v_exp_f32_e32 v9, v9
	v_sub_f32_e32 v10, v73, v147
	v_add_f32_e32 v2, v5, v2
	v_cvt_pk_bf16_f32 v82, v11, v12
	v_exp_f32_e32 v10, v10
	v_sub_f32_e32 v11, v74, v147
	v_add_f32_e32 v2, v6, v2
	v_exp_f32_e32 v11, v11
	v_sub_f32_e32 v12, v75, v147
	v_add_f32_e32 v2, v7, v2
	v_cvt_pk_bf16_f32 v83, v13, v14
	v_exp_f32_e32 v12, v12
	v_sub_f32_e32 v13, v76, v147
	v_add_f32_e32 v2, v8, v2
	v_exp_f32_e32 v13, v13
	v_sub_f32_e32 v14, v77, v147
	v_add_f32_e32 v2, v9, v2
	v_cvt_pk_bf16_f32 v84, v15, v16
	v_exp_f32_e32 v14, v14
	v_sub_f32_e32 v15, v78, v147
	v_add_f32_e32 v2, v10, v2
	v_exp_f32_e32 v15, v15
	v_sub_f32_e32 v16, v79, v147
	v_add_f32_e32 v2, v11, v2
	v_cvt_pk_bf16_f32 v85, v17, v18
	v_exp_f32_e32 v16, v16
	v_sub_f32_e32 v17, v80, v147
	v_add_f32_e32 v2, v12, v2
	v_exp_f32_e32 v17, v17
	v_sub_f32_e32 v18, v81, v147
	v_add_f32_e32 v2, v13, v2
	v_exp_f32_e32 v18, v18
	v_cvt_pk_bf16_f32 v70, v3, v4
	v_add_f32_e32 v2, v14, v2
	v_sub_f32_e32 v3, v50, v147
	v_add_f32_e32 v2, v15, v2
	v_exp_f32_e32 v3, v3
	v_sub_f32_e32 v4, v51, v147
	v_cvt_pk_bf16_f32 v71, v5, v6
	v_add_f32_e32 v2, v16, v2
	v_exp_f32_e32 v4, v4
	v_sub_f32_e32 v5, v52, v147
	v_add_f32_e32 v2, v17, v2
	v_exp_f32_e32 v5, v5
	v_sub_f32_e32 v6, v53, v147
	v_cvt_pk_bf16_f32 v72, v7, v8
	v_add_f32_e32 v2, v18, v2
	v_exp_f32_e32 v6, v6
	v_sub_f32_e32 v7, v54, v147
	v_exp_f32_e32 v7, v7
	v_sub_f32_e32 v8, v55, v147
	v_add_f32_e32 v2, v3, v2
	v_cvt_pk_bf16_f32 v73, v9, v10
	v_exp_f32_e32 v8, v8
	v_sub_f32_e32 v9, v56, v147
	v_add_f32_e32 v2, v4, v2
	v_exp_f32_e32 v9, v9
	v_sub_f32_e32 v10, v57, v147
	v_add_f32_e32 v2, v5, v2
	v_cvt_pk_bf16_f32 v66, v11, v12
	v_exp_f32_e32 v10, v10
	v_sub_f32_e32 v11, v58, v147
	v_add_f32_e32 v2, v6, v2
	v_exp_f32_e32 v11, v11
	v_sub_f32_e32 v12, v59, v147
	v_add_f32_e32 v2, v7, v2
	v_cvt_pk_bf16_f32 v67, v13, v14
	v_exp_f32_e32 v12, v12
	v_sub_f32_e32 v13, v60, v147
	v_add_f32_e32 v2, v8, v2
	v_exp_f32_e32 v13, v13
	v_sub_f32_e32 v14, v61, v147
	v_add_f32_e32 v2, v9, v2
	v_cvt_pk_bf16_f32 v68, v15, v16
	v_exp_f32_e32 v14, v14
	v_sub_f32_e32 v15, v62, v147
	v_add_f32_e32 v2, v10, v2
	v_exp_f32_e32 v15, v15
	v_sub_f32_e32 v16, v63, v147
	v_add_f32_e32 v2, v11, v2
	v_cvt_pk_bf16_f32 v69, v17, v18
	v_exp_f32_e32 v16, v16
	v_sub_f32_e32 v17, v64, v147
	v_add_f32_e32 v2, v12, v2
	v_exp_f32_e32 v17, v17
	v_sub_f32_e32 v18, v65, v147
	v_add_f32_e32 v2, v13, v2
	v_exp_f32_e32 v18, v18
	v_add_f32_e32 v2, v14, v2
	v_add_f32_e32 v2, v15, v2
	v_add_f32_e32 v2, v16, v2
	v_add_f32_e32 v2, v17, v2
	v_add_f32_e32 v2, v18, v2
	v_cvt_pk_bf16_f32 v54, v3, v4
	ds_bpermute_b32 v3, v146, v2
	v_cvt_pk_bf16_f32 v55, v5, v6
	v_cvt_pk_bf16_f32 v56, v7, v8
	v_cvt_pk_bf16_f32 v57, v9, v10
	v_cvt_pk_bf16_f32 v50, v11, v12
	s_waitcnt lgkmcnt(0)
	v_add_f32_e32 v2, v2, v3
	v_div_scale_f32 v3, s[16:17], v2, v2, 1.0
	v_rcp_f32_e32 v4, v3
	v_cvt_pk_bf16_f32 v51, v13, v14
	v_cvt_pk_bf16_f32 v52, v15, v16
	v_cvt_pk_bf16_f32 v53, v17, v18
	v_fma_f32 v5, -v3, v4, 1.0
	v_fmac_f32_e32 v4, v5, v4
	v_div_scale_f32 v5, vcc, 1.0, v2, 1.0
	v_mul_f32_e32 v6, v5, v4
	v_fma_f32 v7, -v3, v6, v5
	v_fmac_f32_e32 v6, v7, v4
	v_fma_f32 v3, -v3, v6, v5
	v_div_fmas_f32 v3, v3, v4, v6
	v_div_fixup_f32 v2, v3, v2, 1.0
